# S5 stage-3 Toeplitz k-loop: reuse A fragments (tiles 2,3 of step k+1 equal tiles 0,1 of step k), 2 of 4 Kt loads per k-step replaced by register moves
# speedup vs baseline: 1.0074x; 1.0074x over previous
; template <int AT, int BT, class FA, class FB>
; DI void wgemm(f32x4 (&acc)[AT][BT], int ksteps, FA fa, FB fb) {
;     ...
;   for (int ks = 0; ks < ksteps; ++ks) {
;     bf16x8 a2[AT], b2[BT];
;     const int kn = (ks + 2 < ksteps) ? ks + 2 : ksteps - 1;
; #pragma unroll
;     for (int i = 0; i < AT; ++i) a2[i] = fa(i, kn);
; #pragma unroll
;     for (int j = 0; j < BT; ++j) b2[j] = fb(j, kn);
; DI void s5_stage3_item(const Params& P, int l, int it, u16* hs, int wave, int lane) {
;     ...
;                 [&](int i, int ks) { const int j = 4 * jg + i, ii = 2 * ks + (q >> 1); const int d = j - ii;
;                                      return (d >= 0) ? ld8(Kt + ((size_t)d * 16 + jn) * 16 + (q & 1) * 8) : zf; },
;                 [&](int jt, int ks) { return ld8(up + ((size_t)(2 * th + jt) * 16 * 64 + 2 * ks) * DINP); });
.LBB0_855:
	s_add_i32 s10, s17, 4
	s_min_i32 s10, s10, s9
	s_lshl_b32 s18, s10, 1
	v_or_b32_e32 v0, s18, v106
	s_waitcnt vmcnt(0)
	v_mov_b64_e32 v[84:85], v[76:77]
	s_waitcnt vmcnt(0)
	v_mov_b64_e32 v[88:89], v[80:81]
	v_sub_u32_e32 v0, s2, v0
	v_mov_b32_e32 v93, v73
	v_mov_b32_e32 v105, v72
	v_mov_b32_e32 v107, v71
	v_mov_b32_e32 v108, v70
	v_mov_b32_e32 v109, v53
	v_mov_b32_e32 v110, v52
	v_mov_b32_e32 v111, v51
	v_mov_b32_e32 v112, v50
	v_mov_b32_e32 v113, v13
	v_mov_b32_e32 v114, v12
	v_mov_b32_e32 v115, v11
	v_mov_b32_e32 v116, v10
	v_mov_b32_e32 v117, v5
	v_mov_b32_e32 v118, v4
	v_mov_b32_e32 v119, v3
	v_mov_b32_e32 v120, v2
	v_mov_b64_e32 v[82:83], v[74:75]
	v_mov_b64_e32 v[86:87], v[78:79]
	v_mov_b64_e32 v[50:51], v[2:3]
	v_mov_b64_e32 v[52:53], v[4:5]
	v_mov_b64_e32 v[70:71], v[10:11]
	v_mov_b64_e32 v[72:73], v[12:13]
	v_cmp_lt_i32_e32 vcc, -1, v0
	v_mov_b32_e32 v2, 0
	v_mov_b32_e32 v3, 0
	v_mov_b32_e32 v4, 0
	v_mov_b32_e32 v5, 0
	s_and_saveexec_b64 s[10:11], vcc
	s_cbranch_execz .LBB0_857
	v_lshlrev_b64 v[2:3], 9, v[0:1]
	v_lshl_add_u64 v[2:3], v[102:103], 0, v[2:3]
	global_load_dwordx4 v[2:5], v[2:3], off
.LBB0_857:
	s_or_b64 exec, exec, s[10:11]
	v_add_u32_e32 v232, 1, v0
	v_cmp_lt_i32_e32 vcc, -1, v232
	v_mov_b32_e32 v10, 0
	v_mov_b32_e32 v11, 0
	v_mov_b32_e32 v12, 0
	v_mov_b32_e32 v13, 0
	s_and_saveexec_b64 s[10:11], vcc
	s_cbranch_execz .LBB0_859
	v_mov_b32_e32 v233, v1
	v_lshlrev_b64 v[10:11], 9, v[232:233]
	v_lshl_add_u64 v[10:11], v[102:103], 0, v[10:11]
	global_load_dwordx4 v[10:13], v[10:11], off
